# skip grid barrier also between out-GEMM(g0) and norm(g1) (independent phases), WG barrier instead
# baseline (speedup 1.0000x reference)
; __global__ void __launch_bounds__(NTHR, 2) fwd_kernel(Args a) {
;     ...
;         if (ph + 1 < a.ph_hi) {
;             if (!xb_ready) { grid.sync(); xb = xcd_barrier_post(barw, bst); xb_ready = true; }
;             else { xcd_barrier(xb); if (DUP_K == 100) { xcd_barrier(xb); xcd_barrier(xb); } }
;         }
.LBB0_475:
	s_add_i32 s92, s92, 1
	s_mov_b64 s[4:5], -1
	s_cmp_ge_i32 s92, s93
	s_mov_b64 s[0:1], -1
	s_cbranch_scc1 .Lhop_15
	s_cmp_eq_u32 s92, 1
	s_cbranch_scc1 .Lmy_skipbar
	s_cmp_eq_u32 s92, 19
	s_cbranch_scc1 .Lmy_skipbar
	s_cmp_eq_u32 s92, 8
	s_cbranch_scc1 .Lmy_skipbar
	s_cmp_eq_u32 s92, 26
	s_cbranch_scc0 .Lmy_noskip
.Lmy_skipbar:
	v_readlane_b32 s4, v255, 5
	v_readlane_b32 s5, v255, 6
	s_waitcnt vmcnt(0) lgkmcnt(0)
	s_barrier
	s_mov_b64 s[0:1], 0
	s_branch .Lhop_15
